# grid barrier: this CU's L1 invalidate issued right after arrival (overlaps the wait) instead of after the generation flips
# baseline (speedup 1.0000x reference)
.LBB0_1934:
	s_or_b64 exec, exec, s[2:3]
	v_cvt_f32_u32_e32 v5, v3
	s_waitcnt vmcnt(0)
	buffer_inv sc1
	v_readfirstlane_b32 s2, v4
	v_sub_u32_e32 v4, 0, v3
	v_rcp_iflag_f32_e32 v5, v5
	v_add_u32_e32 v6, s2, v0
	v_mul_f32_e32 v5, 0x4f7ffffe, v5
	v_cvt_u32_f32_e32 v5, v5
	v_mul_lo_u32 v0, v4, v5
	v_mul_hi_u32 v0, v5, v0
	v_add_u32_e32 v0, v5, v0
	v_mul_hi_u32 v0, v6, v0
	v_mul_lo_u32 v4, v0, v3
	v_sub_u32_e32 v4, v6, v4
	v_add_u32_e32 v5, 1, v0
	v_cmp_ge_u32_e32 vcc, v4, v3
	s_nop 1
	v_cndmask_b32_e32 v0, v0, v5, vcc
	v_sub_u32_e32 v5, v4, v3
	v_cndmask_b32_e32 v4, v4, v5, vcc
	v_add_u32_e32 v5, 1, v0
	v_cmp_ge_u32_e32 vcc, v4, v3
	v_add_u32_e32 v4, 1, v6
	s_nop 0
	v_cndmask_b32_e32 v0, v0, v5, vcc
	v_mul_lo_u32 v5, v3, v0
	v_add_u32_e32 v3, v5, v3
	v_cmp_ne_u32_e32 vcc, v4, v3
	s_and_saveexec_b64 s[2:3], vcc
	s_xor_b64 s[2:3], exec, s[2:3]
	s_cbranch_execz .LBB0_1948
	v_readlane_b32 s4, v254, 29
	v_readlane_b32 s5, v254, 30
	s_waitcnt lgkmcnt(0)
	s_nop 3
	global_load_dword v2, v1, s[4:5] sc1
	s_waitcnt vmcnt(0)
	v_cmp_eq_u32_e32 vcc, v2, v0
	s_and_saveexec_b64 s[4:5], vcc
	s_cbranch_execz .LBB0_1947
	s_mov_b32 s17, 1
	s_mov_b64 s[6:7], 0
	s_branch .LBB0_1938

.LBB0_1947:
	s_or_b64 exec, exec, s[4:5]
	s_waitcnt vmcnt(0)
	s_waitcnt vmcnt(0)

.LBB0_1965:
	s_or_b64 exec, exec, s[2:3]
	s_mov_b64 s[2:3], exec
	v_mbcnt_lo_u32_b32 v0, s2, 0
	v_mbcnt_hi_u32_b32 v0, s3, v0
	v_cmp_eq_u32_e32 vcc, 0, v0
	s_waitcnt vmcnt(0)
	s_and_saveexec_b64 s[4:5], vcc
	s_cbranch_execz .LBB0_1967
	s_bcnt1_i32_b64 s2, s[2:3]
	v_mov_b32_e32 v0, s2
	v_readlane_b32 s2, v254, 25
	v_readlane_b32 s3, v254, 26
	s_nop 4
